# N2: N1 + the shared out/ff2 K-loop also skips the dummy next-unit prefetch DMAs in the final unit's last iteration
# baseline (speedup 1.0000x reference)
.LBB0_389:
	s_add_i32 s87, s6, 2
	s_add_u32 s26, s0, 0x80
	s_addc_u32 s7, s1, 0
	s_add_i32 s88, 0, 0x10000
	s_cmp_eq_u32 s84, s6
	s_cselect_b32 s7, s35, s7
	s_cselect_b32 s6, s34, s26
	v_add_u32_e32 v144, s88, v146
	s_cselect_b32 s27, s39, s31
	s_cselect_b32 s26, s38, s23
	s_cselect_b32 s100, 1, 0
	s_cmp_lg_u64 s[36:37], 0
	s_cselect_b32 s100, 0, s100
	s_add_i32 s89, 0, 0x14000
	.p2align 6
	ds_read_b128 v[140:143], v144
	ds_read_b128 v[148:151], v144 offset:1024
	ds_read_b128 v[152:155], v144 offset:2048
	ds_read_b128 v[156:159], v144 offset:3072
	v_add_u32_e32 v144, s89, v146
	ds_read_b128 v[160:163], v144
	ds_read_b128 v[164:167], v144 offset:1024
	ds_read_b128 v[168:171], v144 offset:2048
	ds_read_b128 v[172:175], v144 offset:3072
	v_lshl_add_u64 v[144:145], s[0:1], 0, v[138:139]
	s_add_i32 m0, s65, 0xc000
	ds_read_b128 v[176:179], v147
	ds_read_b128 v[180:183], v147 offset:1024
	ds_read_b128 v[188:191], v147 offset:2048
	ds_read_b128 v[192:195], v147 offset:3072
	ds_read_b128 v[196:199], v147 offset:4096
	ds_read_b128 v[200:203], v147 offset:5120
	ds_read_b128 v[204:207], v147 offset:6144
	ds_read_b128 v[208:211], v147 offset:7168
	global_load_lds_dwordx4 v[144:145], off
	v_lshl_add_u64 v[144:145], s[0:1], 0, v[136:137]
	s_add_i32 m0, s65, 0xe000
	s_nop 0
	global_load_lds_dwordx4 v[144:145], off
	s_waitcnt vmcnt(8)
	s_waitcnt lgkmcnt(0)
	s_barrier
	s_setprio 1
	s_waitcnt lgkmcnt(0)
	v_mfma_f32_16x16x32_bf16 v[126:129], v[140:143], v[176:179], v[126:129]
	v_mfma_f32_16x16x32_bf16 v[122:125], v[152:155], v[176:179], v[122:125]
	v_mfma_f32_16x16x32_bf16 v[114:117], v[140:143], v[188:191], v[114:117]
	v_mfma_f32_16x16x32_bf16 v[106:109], v[152:155], v[188:191], v[106:109]
	v_mfma_f32_16x16x32_bf16 v[98:101], v[140:143], v[196:199], v[98:101]
	v_mfma_f32_16x16x32_bf16 v[90:93], v[152:155], v[196:199], v[90:93]
	v_mfma_f32_16x16x32_bf16 v[82:85], v[140:143], v[204:207], v[82:85]
	v_mfma_f32_16x16x32_bf16 v[72:75], v[152:155], v[204:207], v[72:75]
	v_mfma_f32_16x16x32_bf16 v[126:129], v[148:151], v[180:183], v[126:129]
	v_mfma_f32_16x16x32_bf16 v[122:125], v[156:159], v[180:183], v[122:125]
	v_mfma_f32_16x16x32_bf16 v[114:117], v[148:151], v[192:195], v[114:117]
	v_mfma_f32_16x16x32_bf16 v[106:109], v[156:159], v[192:195], v[106:109]
	v_mfma_f32_16x16x32_bf16 v[98:101], v[148:151], v[200:203], v[98:101]
	v_mfma_f32_16x16x32_bf16 v[90:93], v[156:159], v[200:203], v[90:93]
	v_mfma_f32_16x16x32_bf16 v[82:85], v[148:151], v[208:211], v[82:85]
	v_mfma_f32_16x16x32_bf16 v[72:75], v[156:159], v[208:211], v[72:75]
	s_setprio 0
	s_setprio 1
	v_mfma_f32_16x16x32_bf16 v[118:121], v[160:163], v[176:179], v[118:121]
	v_mfma_f32_16x16x32_bf16 v[110:113], v[168:171], v[176:179], v[110:113]
	v_mfma_f32_16x16x32_bf16 v[102:105], v[160:163], v[188:191], v[102:105]
	v_mfma_f32_16x16x32_bf16 v[94:97], v[168:171], v[188:191], v[94:97]
	v_mfma_f32_16x16x32_bf16 v[86:89], v[160:163], v[196:199], v[86:89]
	v_mfma_f32_16x16x32_bf16 v[76:79], v[168:171], v[196:199], v[76:79]
	v_mfma_f32_16x16x32_bf16 v[68:71], v[160:163], v[204:207], v[68:71]
	v_mfma_f32_16x16x32_bf16 v[64:67], v[168:171], v[204:207], v[64:67]
	v_mfma_f32_16x16x32_bf16 v[118:121], v[164:167], v[180:183], v[118:121]
	v_mfma_f32_16x16x32_bf16 v[110:113], v[172:175], v[180:183], v[110:113]
	v_mfma_f32_16x16x32_bf16 v[102:105], v[164:167], v[192:195], v[102:105]
	v_mfma_f32_16x16x32_bf16 v[94:97], v[172:175], v[192:195], v[94:97]
	v_mfma_f32_16x16x32_bf16 v[86:89], v[164:167], v[200:203], v[86:89]
	v_mfma_f32_16x16x32_bf16 v[76:79], v[172:175], v[200:203], v[76:79]
	v_mfma_f32_16x16x32_bf16 v[68:71], v[164:167], v[208:211], v[68:71]
	v_mfma_f32_16x16x32_bf16 v[64:67], v[172:175], v[208:211], v[64:67]
	s_setprio 0
	s_barrier
	s_add_i32 s88, s88, s63
	v_lshl_add_u64 v[144:145], s[26:27], 0, v[80:81]
	s_mov_b32 m0, s88
	ds_read_b128 v[176:179], v147 offset:16384
	ds_read_b128 v[180:183], v147 offset:17408
	ds_read_b128 v[188:191], v147 offset:18432
	ds_read_b128 v[192:195], v147 offset:19456
	ds_read_b128 v[196:199], v147 offset:20480
	ds_read_b128 v[200:203], v147 offset:21504
	ds_read_b128 v[204:207], v147 offset:22528
	ds_read_b128 v[208:211], v147 offset:23552
	s_cmp_eq_u32 s100, 1
	s_cbranch_scc1 .Ln2_k47_sp2
	global_load_lds_dwordx4 v[144:145], off
	s_add_i32 m0, s88, 0x2000
	v_lshl_add_u64 v[184:185], s[26:27], 0, v[130:131]
	s_add_u32 s26, s26, s18
	s_addc_u32 s27, s27, 0
	s_add_i32 s88, s89, s63
	global_load_lds_dwordx4 v[184:185], off
	v_lshl_add_u64 v[186:187], s[26:27], 0, v[80:81]
	s_mov_b32 m0, s88
	v_lshl_add_u64 v[212:213], s[26:27], 0, v[130:131]
	global_load_lds_dwordx4 v[186:187], off
	s_add_i32 m0, s88, 0x2000
	v_lshl_add_u64 v[214:215], s[6:7], 0, v[134:135]
	global_load_lds_dwordx4 v[212:213], off
	s_mov_b32 m0, s65
	v_lshl_add_u64 v[220:221], s[6:7], 0, v[132:133]
	global_load_lds_dwordx4 v[214:215], off
	s_mov_b32 m0, s66
	s_nop 0
	global_load_lds_dwordx4 v[220:221], off
	s_waitcnt vmcnt(8)
	s_branch .Ln2_k47_sp2_j

.Ln2_k47_sp2_j:
	s_waitcnt lgkmcnt(0)
	s_barrier
	s_setprio 1
	s_waitcnt lgkmcnt(0)
	v_mfma_f32_16x16x32_bf16 v[60:63], v[140:143], v[176:179], v[60:63]
	v_mfma_f32_16x16x32_bf16 v[56:59], v[152:155], v[176:179], v[56:59]
	v_mfma_f32_16x16x32_bf16 v[48:51], v[140:143], v[188:191], v[48:51]
	v_mfma_f32_16x16x32_bf16 v[40:43], v[152:155], v[188:191], v[40:43]
	v_mfma_f32_16x16x32_bf16 v[32:35], v[140:143], v[196:199], v[32:35]
	v_mfma_f32_16x16x32_bf16 v[24:27], v[152:155], v[196:199], v[24:27]
	v_mfma_f32_16x16x32_bf16 v[16:19], v[140:143], v[204:207], v[16:19]
	v_mfma_f32_16x16x32_bf16 v[8:11], v[152:155], v[204:207], v[8:11]
	v_mfma_f32_16x16x32_bf16 v[60:63], v[148:151], v[180:183], v[60:63]
	v_mfma_f32_16x16x32_bf16 v[56:59], v[156:159], v[180:183], v[56:59]
	v_mfma_f32_16x16x32_bf16 v[48:51], v[148:151], v[192:195], v[48:51]
	v_mfma_f32_16x16x32_bf16 v[40:43], v[156:159], v[192:195], v[40:43]
	v_mfma_f32_16x16x32_bf16 v[32:35], v[148:151], v[200:203], v[32:35]
	v_mfma_f32_16x16x32_bf16 v[24:27], v[156:159], v[200:203], v[24:27]
	v_mfma_f32_16x16x32_bf16 v[16:19], v[148:151], v[208:211], v[16:19]
	v_mfma_f32_16x16x32_bf16 v[8:11], v[156:159], v[208:211], v[8:11]
	s_setprio 0
	s_setprio 1
	v_mfma_f32_16x16x32_bf16 v[52:55], v[160:163], v[176:179], v[52:55]
	v_mfma_f32_16x16x32_bf16 v[44:47], v[168:171], v[176:179], v[44:47]
	v_mfma_f32_16x16x32_bf16 v[36:39], v[160:163], v[188:191], v[36:39]
	v_mfma_f32_16x16x32_bf16 v[28:31], v[168:171], v[188:191], v[28:31]
	v_mfma_f32_16x16x32_bf16 v[20:23], v[160:163], v[196:199], v[20:23]
	v_mfma_f32_16x16x32_bf16 v[12:15], v[168:171], v[196:199], v[12:15]
	v_mfma_f32_16x16x32_bf16 v[4:7], v[160:163], v[204:207], v[4:7]
	v_mfma_f32_16x16x32_bf16 v[0:3], v[168:171], v[204:207], v[0:3]
	v_mfma_f32_16x16x32_bf16 v[52:55], v[164:167], v[180:183], v[52:55]
	v_mfma_f32_16x16x32_bf16 v[44:47], v[172:175], v[180:183], v[44:47]
	v_mfma_f32_16x16x32_bf16 v[36:39], v[164:167], v[192:195], v[36:39]
	v_mfma_f32_16x16x32_bf16 v[28:31], v[172:175], v[192:195], v[28:31]
	v_mfma_f32_16x16x32_bf16 v[20:23], v[164:167], v[200:203], v[20:23]
	v_mfma_f32_16x16x32_bf16 v[12:15], v[172:175], v[200:203], v[12:15]
	v_mfma_f32_16x16x32_bf16 v[4:7], v[164:167], v[208:211], v[4:7]
	v_mfma_f32_16x16x32_bf16 v[0:3], v[172:175], v[208:211], v[0:3]
	s_setprio 0
	s_barrier
	s_add_i32 s26, 0, 0x18000
	s_add_i32 s27, 0, 0x1c000
	v_add_u32_e32 v156, s26, v146
	v_add_u32_e32 v172, s27, v146
	ds_read_b128 v[140:143], v156
	ds_read_b128 v[148:151], v156 offset:1024
	ds_read_b128 v[152:155], v156 offset:2048
	ds_read_b128 v[156:159], v156 offset:3072
	ds_read_b128 v[160:163], v172
	ds_read_b128 v[164:167], v172 offset:1024
	ds_read_b128 v[168:171], v172 offset:2048
	ds_read_b128 v[172:175], v172 offset:3072
	s_add_u32 s6, s6, s18
	s_addc_u32 s7, s7, 0
	s_mov_b32 m0, s67
	v_lshl_add_u64 v[222:223], s[6:7], 0, v[134:135]
	ds_read_b128 v[176:179], v147 offset:32768
	ds_read_b128 v[180:183], v147 offset:33792
	ds_read_b128 v[188:191], v147 offset:34816
	ds_read_b128 v[192:195], v147 offset:35840
	ds_read_b128 v[196:199], v147 offset:36864
	ds_read_b128 v[200:203], v147 offset:37888
	ds_read_b128 v[204:207], v147 offset:38912
	ds_read_b128 v[208:211], v147 offset:39936
	s_cmp_eq_u32 s100, 1
	s_cbranch_scc1 .Ln2_k47_sp3
	global_load_lds_dwordx4 v[222:223], off
	v_lshl_add_u64 v[222:223], s[6:7], 0, v[132:133]
	s_mov_b32 m0, s70
	s_nop 0
	global_load_lds_dwordx4 v[222:223], off
	s_waitcnt vmcnt(8)
	s_branch .Ln2_k47_sp3_j

.Ln2_k47_sp3_j:
	s_waitcnt lgkmcnt(0)
	s_barrier
	s_setprio 1
	s_waitcnt lgkmcnt(0)
	v_mfma_f32_16x16x32_bf16 v[126:129], v[140:143], v[176:179], v[126:129]
	v_mfma_f32_16x16x32_bf16 v[122:125], v[152:155], v[176:179], v[122:125]
	v_mfma_f32_16x16x32_bf16 v[114:117], v[140:143], v[188:191], v[114:117]
	v_mfma_f32_16x16x32_bf16 v[106:109], v[152:155], v[188:191], v[106:109]
	v_mfma_f32_16x16x32_bf16 v[98:101], v[140:143], v[196:199], v[98:101]
	v_mfma_f32_16x16x32_bf16 v[90:93], v[152:155], v[196:199], v[90:93]
	v_mfma_f32_16x16x32_bf16 v[82:85], v[140:143], v[204:207], v[82:85]
	v_mfma_f32_16x16x32_bf16 v[72:75], v[152:155], v[204:207], v[72:75]
	v_mfma_f32_16x16x32_bf16 v[126:129], v[148:151], v[180:183], v[126:129]
	v_mfma_f32_16x16x32_bf16 v[122:125], v[156:159], v[180:183], v[122:125]
	v_mfma_f32_16x16x32_bf16 v[114:117], v[148:151], v[192:195], v[114:117]
	v_mfma_f32_16x16x32_bf16 v[106:109], v[156:159], v[192:195], v[106:109]
	v_mfma_f32_16x16x32_bf16 v[98:101], v[148:151], v[200:203], v[98:101]
	v_mfma_f32_16x16x32_bf16 v[90:93], v[156:159], v[200:203], v[90:93]
	v_mfma_f32_16x16x32_bf16 v[82:85], v[148:151], v[208:211], v[82:85]
	v_mfma_f32_16x16x32_bf16 v[72:75], v[156:159], v[208:211], v[72:75]
	s_setprio 0
	s_setprio 1
	v_mfma_f32_16x16x32_bf16 v[118:121], v[160:163], v[176:179], v[118:121]
	v_mfma_f32_16x16x32_bf16 v[110:113], v[168:171], v[176:179], v[110:113]
	v_mfma_f32_16x16x32_bf16 v[102:105], v[160:163], v[188:191], v[102:105]
	v_mfma_f32_16x16x32_bf16 v[94:97], v[168:171], v[188:191], v[94:97]
	v_mfma_f32_16x16x32_bf16 v[86:89], v[160:163], v[196:199], v[86:89]
	v_mfma_f32_16x16x32_bf16 v[76:79], v[168:171], v[196:199], v[76:79]
	v_mfma_f32_16x16x32_bf16 v[68:71], v[160:163], v[204:207], v[68:71]
	v_mfma_f32_16x16x32_bf16 v[64:67], v[168:171], v[204:207], v[64:67]
	v_mfma_f32_16x16x32_bf16 v[118:121], v[164:167], v[180:183], v[118:121]
	v_mfma_f32_16x16x32_bf16 v[110:113], v[172:175], v[180:183], v[110:113]
	v_mfma_f32_16x16x32_bf16 v[102:105], v[164:167], v[192:195], v[102:105]
	v_mfma_f32_16x16x32_bf16 v[94:97], v[172:175], v[192:195], v[94:97]
	v_mfma_f32_16x16x32_bf16 v[86:89], v[164:167], v[200:203], v[86:89]
	v_mfma_f32_16x16x32_bf16 v[76:79], v[172:175], v[200:203], v[76:79]
	v_mfma_f32_16x16x32_bf16 v[68:71], v[164:167], v[208:211], v[68:71]
	v_mfma_f32_16x16x32_bf16 v[64:67], v[172:175], v[208:211], v[64:67]
	s_setprio 0
	s_barrier
	s_add_i32 s6, s26, s63
	v_lshl_add_u64 v[144:145], v[144:145], 0, s[12:13]
	s_mov_b32 m0, s6
	ds_read_b128 v[176:179], v147 offset:49152
	ds_read_b128 v[180:183], v147 offset:50176
	ds_read_b128 v[188:191], v147 offset:51200
	ds_read_b128 v[192:195], v147 offset:52224
	ds_read_b128 v[196:199], v147 offset:53248
	ds_read_b128 v[200:203], v147 offset:54272
	ds_read_b128 v[204:207], v147 offset:55296
	ds_read_b128 v[208:211], v147 offset:56320
	s_cmp_eq_u32 s100, 1
	s_cbranch_scc1 .Ln2_k47_sp4
	global_load_lds_dwordx4 v[144:145], off
	v_lshl_add_u64 v[144:145], v[184:185], 0, s[12:13]
	s_add_i32 m0, s6, 0x2000
	s_add_i32 s6, s27, s63
	global_load_lds_dwordx4 v[144:145], off
	v_lshl_add_u64 v[144:145], v[186:187], 0, s[12:13]
	s_mov_b32 m0, s6
	s_nop 0
	global_load_lds_dwordx4 v[144:145], off
	v_lshl_add_u64 v[144:145], v[212:213], 0, s[12:13]
	s_add_i32 m0, s6, 0x2000
	s_nop 0
	global_load_lds_dwordx4 v[144:145], off
	v_lshl_add_u64 v[144:145], v[214:215], 0, s[12:13]
	s_mov_b32 m0, s82
	s_nop 0
	global_load_lds_dwordx4 v[144:145], off
	v_lshl_add_u64 v[144:145], v[220:221], 0, s[12:13]
	s_mov_b32 m0, s83
	s_nop 0
	global_load_lds_dwordx4 v[144:145], off
	s_waitcnt vmcnt(8)
	s_branch .Ln2_k47_sp4_j
.Ln2_k47_sp4:
.Ln2_k47_sp4_j:
	s_waitcnt lgkmcnt(0)
	s_barrier
	s_setprio 1
	s_waitcnt lgkmcnt(0)
	v_mfma_f32_16x16x32_bf16 v[60:63], v[140:143], v[176:179], v[60:63]
	v_mfma_f32_16x16x32_bf16 v[56:59], v[152:155], v[176:179], v[56:59]
	v_mfma_f32_16x16x32_bf16 v[48:51], v[140:143], v[188:191], v[48:51]
	v_mfma_f32_16x16x32_bf16 v[40:43], v[152:155], v[188:191], v[40:43]
	v_mfma_f32_16x16x32_bf16 v[32:35], v[140:143], v[196:199], v[32:35]
	v_mfma_f32_16x16x32_bf16 v[24:27], v[152:155], v[196:199], v[24:27]
	v_mfma_f32_16x16x32_bf16 v[16:19], v[140:143], v[204:207], v[16:19]
	v_mfma_f32_16x16x32_bf16 v[8:11], v[152:155], v[204:207], v[8:11]
	v_mfma_f32_16x16x32_bf16 v[60:63], v[148:151], v[180:183], v[60:63]
	v_mfma_f32_16x16x32_bf16 v[56:59], v[156:159], v[180:183], v[56:59]
	v_mfma_f32_16x16x32_bf16 v[48:51], v[148:151], v[192:195], v[48:51]
	v_mfma_f32_16x16x32_bf16 v[40:43], v[156:159], v[192:195], v[40:43]
	v_mfma_f32_16x16x32_bf16 v[32:35], v[148:151], v[200:203], v[32:35]
	v_mfma_f32_16x16x32_bf16 v[24:27], v[156:159], v[200:203], v[24:27]
	v_mfma_f32_16x16x32_bf16 v[16:19], v[148:151], v[208:211], v[16:19]
	v_mfma_f32_16x16x32_bf16 v[8:11], v[156:159], v[208:211], v[8:11]
	s_setprio 0
	s_setprio 1
	v_mfma_f32_16x16x32_bf16 v[52:55], v[160:163], v[176:179], v[52:55]
	v_mfma_f32_16x16x32_bf16 v[44:47], v[168:171], v[176:179], v[44:47]
	v_mfma_f32_16x16x32_bf16 v[36:39], v[160:163], v[188:191], v[36:39]
	v_mfma_f32_16x16x32_bf16 v[28:31], v[168:171], v[188:191], v[28:31]
	v_mfma_f32_16x16x32_bf16 v[20:23], v[160:163], v[196:199], v[20:23]
	v_mfma_f32_16x16x32_bf16 v[12:15], v[168:171], v[196:199], v[12:15]
	v_mfma_f32_16x16x32_bf16 v[4:7], v[160:163], v[204:207], v[4:7]
	v_mfma_f32_16x16x32_bf16 v[0:3], v[168:171], v[204:207], v[0:3]
	v_mfma_f32_16x16x32_bf16 v[52:55], v[164:167], v[180:183], v[52:55]
	v_mfma_f32_16x16x32_bf16 v[44:47], v[172:175], v[180:183], v[44:47]
	v_mfma_f32_16x16x32_bf16 v[36:39], v[164:167], v[192:195], v[36:39]
	v_mfma_f32_16x16x32_bf16 v[28:31], v[172:175], v[192:195], v[28:31]
	v_mfma_f32_16x16x32_bf16 v[20:23], v[164:167], v[200:203], v[20:23]
	v_mfma_f32_16x16x32_bf16 v[12:15], v[172:175], v[200:203], v[12:15]
	v_mfma_f32_16x16x32_bf16 v[4:7], v[164:167], v[208:211], v[4:7]
	v_mfma_f32_16x16x32_bf16 v[0:3], v[172:175], v[208:211], v[0:3]
	s_setprio 0
	s_barrier
	s_add_u32 s23, s23, 0x100
	s_addc_u32 s31, s31, 0
	s_add_u32 s0, s0, 0x100
	s_addc_u32 s1, s1, 0
	s_cmp_ge_u32 s87, s71
	s_mov_b32 s6, s87
	s_cbranch_scc0 .LBB0_389
	s_and_b64 vcc, exec, s[16:17]
	s_cbranch_vccz .LBB0_392
	s_barrier
